# v24 plus accumulator zeroing at GEMM unit heads as 64 v_mov_b64 of inline 0 instead of 128 v_mov_b32 (11 sites)
# speedup vs baseline: 1.0032x; 1.0032x over previous
.LBB0_379:
	s_add_u32 s4, s30, 0x100
	s_addc_u32 s5, s31, 0
	s_add_u32 s11, s28, 0x100
	s_addc_u32 s13, s29, 0
	s_add_u32 s28, s30, 0x80080
	v_mov_b64_e32 v[0:1], 0
	s_addc_u32 s29, s31, 0
	s_mov_b32 s15, -2
	v_mov_b64_e32 v[2:3], 0
	v_mov_b64_e32 v[4:5], 0
	v_mov_b64_e32 v[6:7], 0
	v_mov_b64_e32 v[8:9], 0
	v_mov_b64_e32 v[10:11], 0
	v_mov_b64_e32 v[16:17], 0
	v_mov_b64_e32 v[18:19], 0
	v_mov_b64_e32 v[24:25], 0
	v_mov_b64_e32 v[26:27], 0
	v_mov_b64_e32 v[32:33], 0
	v_mov_b64_e32 v[34:35], 0
	v_mov_b64_e32 v[40:41], 0
	v_mov_b64_e32 v[42:43], 0
	v_mov_b64_e32 v[48:49], 0
	v_mov_b64_e32 v[50:51], 0
	v_mov_b64_e32 v[12:13], 0
	v_mov_b64_e32 v[14:15], 0
	v_mov_b64_e32 v[20:21], 0
	v_mov_b64_e32 v[22:23], 0
	v_mov_b64_e32 v[28:29], 0
	v_mov_b64_e32 v[30:31], 0
	v_mov_b64_e32 v[36:37], 0
	v_mov_b64_e32 v[38:39], 0
	v_mov_b64_e32 v[44:45], 0
	v_mov_b64_e32 v[46:47], 0
	v_mov_b64_e32 v[52:53], 0
	v_mov_b64_e32 v[54:55], 0
	v_mov_b64_e32 v[56:57], 0
	v_mov_b64_e32 v[58:59], 0
	v_mov_b64_e32 v[60:61], 0
	v_mov_b64_e32 v[62:63], 0
	v_mov_b64_e32 v[64:65], 0
	v_mov_b64_e32 v[66:67], 0
	v_mov_b64_e32 v[68:69], 0
	v_mov_b64_e32 v[70:71], 0
	v_mov_b64_e32 v[72:73], 0
	v_mov_b64_e32 v[74:75], 0
	v_mov_b64_e32 v[80:81], 0
	v_mov_b64_e32 v[82:83], 0
	v_mov_b64_e32 v[88:89], 0
	v_mov_b64_e32 v[90:91], 0
	v_mov_b64_e32 v[96:97], 0
	v_mov_b64_e32 v[98:99], 0
	v_mov_b64_e32 v[104:105], 0
	v_mov_b64_e32 v[106:107], 0
	v_mov_b64_e32 v[112:113], 0
	v_mov_b64_e32 v[114:115], 0
	v_mov_b64_e32 v[76:77], 0
	v_mov_b64_e32 v[78:79], 0
	v_mov_b64_e32 v[84:85], 0
	v_mov_b64_e32 v[86:87], 0
	v_mov_b64_e32 v[92:93], 0
	v_mov_b64_e32 v[94:95], 0
	v_mov_b64_e32 v[100:101], 0
	v_mov_b64_e32 v[102:103], 0
	v_mov_b64_e32 v[108:109], 0
	v_mov_b64_e32 v[110:111], 0
	v_mov_b64_e32 v[116:117], 0
	v_mov_b64_e32 v[118:119], 0
	v_mov_b64_e32 v[120:121], 0
	v_mov_b64_e32 v[122:123], 0
	v_mov_b64_e32 v[124:125], 0
	v_mov_b64_e32 v[126:127], 0

.LBB0_396:
	s_ashr_i32 s15, s14, 31
	s_lshl_b64 s[16:17], s[14:15], 18
	s_add_u32 s16, s8, s16
	s_addc_u32 s17, s9, s17
	s_and_b64 s[22:23], s[20:21], exec
	s_cselect_b32 s5, s17, s29
	s_cselect_b32 s15, s16, s28
	s_ashr_i32 s13, s12, 31
	s_lshl_b64 s[22:23], s[12:13], 18
	s_add_u32 s22, s19, s22
	s_addc_u32 s23, s36, s23
	s_and_b64 s[30:31], s[20:21], exec
	s_cselect_b32 s13, s23, s27
	s_cselect_b32 s48, s22, s26
	s_add_u32 s49, s28, 0x100
	s_addc_u32 s56, s29, 0
	s_add_u32 s57, s26, 0x100
	s_addc_u32 s65, s27, 0
	s_add_u32 s26, s28, 0x20080
	v_mov_b64_e32 v[0:1], 0
	s_addc_u32 s27, s29, 0
	s_mov_b32 s69, -2
	v_mov_b64_e32 v[2:3], 0
	v_mov_b64_e32 v[4:5], 0
	v_mov_b64_e32 v[6:7], 0
	v_mov_b64_e32 v[8:9], 0
	v_mov_b64_e32 v[10:11], 0
	v_mov_b64_e32 v[16:17], 0
	v_mov_b64_e32 v[18:19], 0
	v_mov_b64_e32 v[24:25], 0
	v_mov_b64_e32 v[26:27], 0
	v_mov_b64_e32 v[32:33], 0
	v_mov_b64_e32 v[34:35], 0
	v_mov_b64_e32 v[40:41], 0
	v_mov_b64_e32 v[42:43], 0
	v_mov_b64_e32 v[48:49], 0
	v_mov_b64_e32 v[50:51], 0
	v_mov_b64_e32 v[12:13], 0
	v_mov_b64_e32 v[14:15], 0
	v_mov_b64_e32 v[20:21], 0
	v_mov_b64_e32 v[22:23], 0
	v_mov_b64_e32 v[28:29], 0
	v_mov_b64_e32 v[30:31], 0
	v_mov_b64_e32 v[36:37], 0
	v_mov_b64_e32 v[38:39], 0
	v_mov_b64_e32 v[44:45], 0
	v_mov_b64_e32 v[46:47], 0
	v_mov_b64_e32 v[52:53], 0
	v_mov_b64_e32 v[54:55], 0
	v_mov_b64_e32 v[56:57], 0
	v_mov_b64_e32 v[58:59], 0
	v_mov_b64_e32 v[60:61], 0
	v_mov_b64_e32 v[62:63], 0
	v_mov_b64_e32 v[64:65], 0
	v_mov_b64_e32 v[66:67], 0
	v_mov_b64_e32 v[68:69], 0
	v_mov_b64_e32 v[70:71], 0
	v_mov_b64_e32 v[72:73], 0
	v_mov_b64_e32 v[74:75], 0
	v_mov_b64_e32 v[80:81], 0
	v_mov_b64_e32 v[82:83], 0
	v_mov_b64_e32 v[88:89], 0
	v_mov_b64_e32 v[90:91], 0
	v_mov_b64_e32 v[96:97], 0
	v_mov_b64_e32 v[98:99], 0
	v_mov_b64_e32 v[104:105], 0
	v_mov_b64_e32 v[106:107], 0
	v_mov_b64_e32 v[112:113], 0
	v_mov_b64_e32 v[114:115], 0
	v_mov_b64_e32 v[76:77], 0
	v_mov_b64_e32 v[78:79], 0
	v_mov_b64_e32 v[84:85], 0
	v_mov_b64_e32 v[86:87], 0
	v_mov_b64_e32 v[92:93], 0
	v_mov_b64_e32 v[94:95], 0
	v_mov_b64_e32 v[100:101], 0
	v_mov_b64_e32 v[102:103], 0
	v_mov_b64_e32 v[108:109], 0
	v_mov_b64_e32 v[110:111], 0
	v_mov_b64_e32 v[116:117], 0
	v_mov_b64_e32 v[118:119], 0
	v_mov_b64_e32 v[120:121], 0
	v_mov_b64_e32 v[122:123], 0
	v_mov_b64_e32 v[124:125], 0
	v_mov_b64_e32 v[126:127], 0

.LBB0_526:
	s_ashr_i32 s85, s84, 31
	s_lshl_b64 s[4:5], s[84:85], 20
	s_add_u32 s80, s47, s4
	s_addc_u32 s81, s65, s5
	s_and_b64 s[4:5], s[34:35], exec
	s_cselect_b32 s4, s81, s13
	s_cselect_b32 s5, s80, s12
	s_ashr_i32 s39, s38, 31
	s_lshl_b64 s[56:57], s[38:39], 20
	s_add_u32 s82, s75, s56
	s_addc_u32 s83, s78, s57
	s_and_b64 s[56:57], s[34:35], exec
	s_cselect_b32 s11, s83, s9
	s_cselect_b32 s37, s82, s8
	s_add_u32 s39, s12, 0x100
	s_addc_u32 s69, s13, 0
	s_add_u32 s72, s8, 0x100
	s_addc_u32 s74, s9, 0
	s_add_u32 s16, s12, 0x80080
	v_mov_b64_e32 v[0:1], 0
	s_addc_u32 s17, s13, 0
	s_mov_b32 s85, -2
	v_mov_b64_e32 v[2:3], 0
	v_mov_b64_e32 v[4:5], 0
	v_mov_b64_e32 v[6:7], 0
	v_mov_b64_e32 v[12:13], 0
	v_mov_b64_e32 v[14:15], 0
	v_mov_b64_e32 v[20:21], 0
	v_mov_b64_e32 v[22:23], 0
	v_mov_b64_e32 v[28:29], 0
	v_mov_b64_e32 v[30:31], 0
	v_mov_b64_e32 v[36:37], 0
	v_mov_b64_e32 v[38:39], 0
	v_mov_b64_e32 v[44:45], 0
	v_mov_b64_e32 v[46:47], 0
	v_mov_b64_e32 v[52:53], 0
	v_mov_b64_e32 v[54:55], 0
	v_mov_b64_e32 v[8:9], 0
	v_mov_b64_e32 v[10:11], 0
	v_mov_b64_e32 v[16:17], 0
	v_mov_b64_e32 v[18:19], 0
	v_mov_b64_e32 v[24:25], 0
	v_mov_b64_e32 v[26:27], 0
	v_mov_b64_e32 v[32:33], 0
	v_mov_b64_e32 v[34:35], 0
	v_mov_b64_e32 v[40:41], 0
	v_mov_b64_e32 v[42:43], 0
	v_mov_b64_e32 v[48:49], 0
	v_mov_b64_e32 v[50:51], 0
	v_mov_b64_e32 v[56:57], 0
	v_mov_b64_e32 v[58:59], 0
	v_mov_b64_e32 v[60:61], 0
	v_mov_b64_e32 v[62:63], 0
	v_mov_b64_e32 v[64:65], 0
	v_mov_b64_e32 v[66:67], 0
	v_mov_b64_e32 v[68:69], 0
	v_mov_b64_e32 v[70:71], 0
	v_mov_b64_e32 v[76:77], 0
	v_mov_b64_e32 v[78:79], 0
	v_mov_b64_e32 v[80:81], 0
	v_mov_b64_e32 v[82:83], 0
	v_mov_b64_e32 v[92:93], 0
	v_mov_b64_e32 v[94:95], 0
	v_mov_b64_e32 v[100:101], 0
	v_mov_b64_e32 v[102:103], 0
	v_mov_b64_e32 v[116:117], 0
	v_mov_b64_e32 v[118:119], 0
	v_mov_b64_e32 v[120:121], 0
	v_mov_b64_e32 v[122:123], 0
	v_mov_b64_e32 v[72:73], 0
	v_mov_b64_e32 v[74:75], 0
	v_mov_b64_e32 v[84:85], 0
	v_mov_b64_e32 v[86:87], 0
	v_mov_b64_e32 v[88:89], 0
	v_mov_b64_e32 v[90:91], 0
	v_mov_b64_e32 v[96:97], 0
	v_mov_b64_e32 v[98:99], 0
	v_mov_b64_e32 v[112:113], 0
	v_mov_b64_e32 v[114:115], 0
	v_mov_b64_e32 v[124:125], 0
	v_mov_b64_e32 v[126:127], 0
	v_mov_b64_e32 v[128:129], 0
	v_mov_b64_e32 v[130:131], 0
	v_mov_b64_e32 v[140:141], 0
	v_mov_b64_e32 v[142:143], 0

.LBB0_603:
	s_add_u32 s4, s36, 0x100
	s_addc_u32 s5, s37, 0
	s_add_u32 s15, s34, 0x100
	v_mov_b64_e32 v[0:1], 0
	s_addc_u32 s17, s35, 0
	s_mov_b32 s21, -2
	v_mov_b64_e32 v[2:3], 0
	v_mov_b64_e32 v[4:5], 0
	v_mov_b64_e32 v[6:7], 0
	v_mov_b64_e32 v[12:13], 0
	v_mov_b64_e32 v[14:15], 0
	v_mov_b64_e32 v[16:17], 0
	v_mov_b64_e32 v[18:19], 0
	v_mov_b64_e32 v[24:25], 0
	v_mov_b64_e32 v[26:27], 0
	v_mov_b64_e32 v[32:33], 0
	v_mov_b64_e32 v[34:35], 0
	v_mov_b64_e32 v[40:41], 0
	v_mov_b64_e32 v[42:43], 0
	v_mov_b64_e32 v[48:49], 0
	v_mov_b64_e32 v[50:51], 0
	v_mov_b64_e32 v[8:9], 0
	v_mov_b64_e32 v[10:11], 0
	v_mov_b64_e32 v[20:21], 0
	v_mov_b64_e32 v[22:23], 0
	v_mov_b64_e32 v[28:29], 0
	v_mov_b64_e32 v[30:31], 0
	v_mov_b64_e32 v[36:37], 0
	v_mov_b64_e32 v[38:39], 0
	v_mov_b64_e32 v[44:45], 0
	v_mov_b64_e32 v[46:47], 0
	v_mov_b64_e32 v[52:53], 0
	v_mov_b64_e32 v[54:55], 0
	v_mov_b64_e32 v[56:57], 0
	v_mov_b64_e32 v[58:59], 0
	v_mov_b64_e32 v[60:61], 0
	v_mov_b64_e32 v[62:63], 0
	v_mov_b64_e32 v[64:65], 0
	v_mov_b64_e32 v[66:67], 0
	v_mov_b64_e32 v[68:69], 0
	v_mov_b64_e32 v[70:71], 0
	v_mov_b64_e32 v[80:81], 0
	v_mov_b64_e32 v[82:83], 0
	v_mov_b64_e32 v[84:85], 0
	v_mov_b64_e32 v[86:87], 0
	v_mov_b64_e32 v[96:97], 0
	v_mov_b64_e32 v[98:99], 0
	v_mov_b64_e32 v[100:101], 0
	v_mov_b64_e32 v[102:103], 0
	v_mov_b64_e32 v[116:117], 0
	v_mov_b64_e32 v[118:119], 0
	v_mov_b64_e32 v[124:125], 0
	v_mov_b64_e32 v[126:127], 0
	v_mov_b64_e32 v[72:73], 0
	v_mov_b64_e32 v[74:75], 0
	v_mov_b64_e32 v[76:77], 0
	v_mov_b64_e32 v[78:79], 0
	v_mov_b64_e32 v[88:89], 0
	v_mov_b64_e32 v[90:91], 0
	v_mov_b64_e32 v[92:93], 0
	v_mov_b64_e32 v[94:95], 0
	v_mov_b64_e32 v[104:105], 0
	v_mov_b64_e32 v[106:107], 0
	v_mov_b64_e32 v[108:109], 0
	v_mov_b64_e32 v[110:111], 0
	v_mov_b64_e32 v[136:137], 0
	v_mov_b64_e32 v[138:139], 0
	v_mov_b64_e32 v[140:141], 0
	v_mov_b64_e32 v[142:143], 0

.LBB0_787:
	s_add_u32 s5, s30, 0x100
	v_mov_b64_e32 v[0:1], 0
	s_addc_u32 s15, s31, 0
	s_mov_b32 s17, -2
	v_mov_b64_e32 v[2:3], 0
	v_mov_b64_e32 v[4:5], 0
	v_mov_b64_e32 v[6:7], 0
	v_mov_b64_e32 v[16:17], 0
	v_mov_b64_e32 v[18:19], 0
	v_mov_b64_e32 v[20:21], 0
	v_mov_b64_e32 v[22:23], 0
	v_mov_b64_e32 v[32:33], 0
	v_mov_b64_e32 v[34:35], 0
	v_mov_b64_e32 v[36:37], 0
	v_mov_b64_e32 v[38:39], 0
	v_mov_b64_e32 v[48:49], 0
	v_mov_b64_e32 v[50:51], 0
	v_mov_b64_e32 v[52:53], 0
	v_mov_b64_e32 v[54:55], 0
	v_mov_b64_e32 v[8:9], 0
	v_mov_b64_e32 v[10:11], 0
	v_mov_b64_e32 v[12:13], 0
	v_mov_b64_e32 v[14:15], 0
	v_mov_b64_e32 v[24:25], 0
	v_mov_b64_e32 v[26:27], 0
	v_mov_b64_e32 v[28:29], 0
	v_mov_b64_e32 v[30:31], 0
	v_mov_b64_e32 v[40:41], 0
	v_mov_b64_e32 v[42:43], 0
	v_mov_b64_e32 v[44:45], 0
	v_mov_b64_e32 v[46:47], 0
	v_mov_b64_e32 v[56:57], 0
	v_mov_b64_e32 v[58:59], 0
	v_mov_b64_e32 v[60:61], 0
	v_mov_b64_e32 v[62:63], 0
	v_mov_b64_e32 v[64:65], 0
	v_mov_b64_e32 v[66:67], 0
	v_mov_b64_e32 v[68:69], 0
	v_mov_b64_e32 v[70:71], 0
	v_mov_b64_e32 v[80:81], 0
	v_mov_b64_e32 v[82:83], 0
	v_mov_b64_e32 v[84:85], 0
	v_mov_b64_e32 v[86:87], 0
	v_mov_b64_e32 v[96:97], 0
	v_mov_b64_e32 v[98:99], 0
	v_mov_b64_e32 v[100:101], 0
	v_mov_b64_e32 v[102:103], 0
	v_mov_b64_e32 v[112:113], 0
	v_mov_b64_e32 v[114:115], 0
	v_mov_b64_e32 v[116:117], 0
	v_mov_b64_e32 v[118:119], 0
	v_mov_b64_e32 v[72:73], 0
	v_mov_b64_e32 v[74:75], 0
	v_mov_b64_e32 v[76:77], 0
	v_mov_b64_e32 v[78:79], 0
	v_mov_b64_e32 v[88:89], 0
	v_mov_b64_e32 v[90:91], 0
	v_mov_b64_e32 v[92:93], 0
	v_mov_b64_e32 v[94:95], 0
	v_mov_b64_e32 v[104:105], 0
	v_mov_b64_e32 v[106:107], 0
	v_mov_b64_e32 v[108:109], 0
	v_mov_b64_e32 v[110:111], 0
	v_mov_b64_e32 v[120:121], 0
	v_mov_b64_e32 v[122:123], 0
	v_mov_b64_e32 v[124:125], 0
	v_mov_b64_e32 v[126:127], 0

.LBB0_1049:
	s_ashr_i32 s37, s36, 31
	s_lshl_b64 s[4:5], s[36:37], 20
	s_add_u32 s40, s19, s4
	s_addc_u32 s41, s65, s5
	s_and_b64 s[4:5], s[34:35], exec
	s_cselect_b32 s4, s41, s13
	s_cselect_b32 s5, s40, s12
	s_ashr_i32 s39, s38, 31
	s_lshl_b64 s[46:47], s[38:39], 20
	s_add_u32 s46, s78, s46
	s_addc_u32 s47, s89, s47
	s_and_b64 s[56:57], s[34:35], exec
	s_cselect_b32 s11, s47, s9
	s_cselect_b32 s37, s46, s8
	s_add_u32 s39, s12, 0x100
	s_addc_u32 s69, s13, 0
	s_add_u32 s72, s8, 0x100
	s_addc_u32 s74, s9, 0
	s_add_u32 s8, s12, 0x80080
	v_mov_b64_e32 v[0:1], 0
	s_addc_u32 s9, s13, 0
	s_mov_b32 s83, -2
	v_mov_b64_e32 v[2:3], 0
	v_mov_b64_e32 v[4:5], 0
	v_mov_b64_e32 v[6:7], 0
	v_mov_b64_e32 v[12:13], 0
	v_mov_b64_e32 v[14:15], 0
	v_mov_b64_e32 v[20:21], 0
	v_mov_b64_e32 v[22:23], 0
	v_mov_b64_e32 v[28:29], 0
	v_mov_b64_e32 v[30:31], 0
	v_mov_b64_e32 v[36:37], 0
	v_mov_b64_e32 v[38:39], 0
	v_mov_b64_e32 v[44:45], 0
	v_mov_b64_e32 v[46:47], 0
	v_mov_b64_e32 v[52:53], 0
	v_mov_b64_e32 v[54:55], 0
	v_mov_b64_e32 v[8:9], 0
	v_mov_b64_e32 v[10:11], 0
	v_mov_b64_e32 v[16:17], 0
	v_mov_b64_e32 v[18:19], 0
	v_mov_b64_e32 v[24:25], 0
	v_mov_b64_e32 v[26:27], 0
	v_mov_b64_e32 v[32:33], 0
	v_mov_b64_e32 v[34:35], 0
	v_mov_b64_e32 v[40:41], 0
	v_mov_b64_e32 v[42:43], 0
	v_mov_b64_e32 v[48:49], 0
	v_mov_b64_e32 v[50:51], 0
	v_mov_b64_e32 v[56:57], 0
	v_mov_b64_e32 v[58:59], 0
	v_mov_b64_e32 v[60:61], 0
	v_mov_b64_e32 v[62:63], 0
	v_mov_b64_e32 v[64:65], 0
	v_mov_b64_e32 v[66:67], 0
	v_mov_b64_e32 v[68:69], 0
	v_mov_b64_e32 v[70:71], 0
	v_mov_b64_e32 v[76:77], 0
	v_mov_b64_e32 v[78:79], 0
	v_mov_b64_e32 v[80:81], 0
	v_mov_b64_e32 v[82:83], 0
	v_mov_b64_e32 v[92:93], 0
	v_mov_b64_e32 v[94:95], 0
	v_mov_b64_e32 v[100:101], 0
	v_mov_b64_e32 v[102:103], 0
	v_mov_b64_e32 v[116:117], 0
	v_mov_b64_e32 v[118:119], 0
	v_mov_b64_e32 v[120:121], 0
	v_mov_b64_e32 v[122:123], 0
	v_mov_b64_e32 v[72:73], 0
	v_mov_b64_e32 v[74:75], 0
	v_mov_b64_e32 v[84:85], 0
	v_mov_b64_e32 v[86:87], 0
	v_mov_b64_e32 v[88:89], 0
	v_mov_b64_e32 v[90:91], 0
	v_mov_b64_e32 v[96:97], 0
	v_mov_b64_e32 v[98:99], 0
	v_mov_b64_e32 v[112:113], 0
	v_mov_b64_e32 v[114:115], 0
	v_mov_b64_e32 v[124:125], 0
	v_mov_b64_e32 v[126:127], 0
	v_mov_b64_e32 v[128:129], 0
	v_mov_b64_e32 v[130:131], 0
	v_mov_b64_e32 v[140:141], 0
	v_mov_b64_e32 v[142:143], 0

.LBB0_1252:
	s_ashr_i32 s27, s26, 31
	s_lshl_b64 s[4:5], s[26:27], 20
	s_add_u32 s28, s65, s4
	s_addc_u32 s29, s70, s5
	s_and_b64 s[4:5], s[22:23], exec
	s_cselect_b32 s4, s29, s11
	s_cselect_b32 s5, s28, s10
	s_ashr_i32 s25, s24, 31
	s_lshl_b64 s[30:31], s[24:25], 20
	s_add_u32 s30, s71, s30
	s_addc_u32 s31, s72, s31
	s_and_b64 s[36:37], s[22:23], exec
	s_cselect_b32 s9, s31, s35
	s_cselect_b32 s25, s30, s34
	s_add_u32 s27, s34, 0x100
	v_mov_b64_e32 v[0:1], 0
	s_addc_u32 vcc_lo, s35, 0
	s_mov_b32 vcc_hi, -2
	v_mov_b64_e32 v[2:3], 0
	v_mov_b64_e32 v[64:65], 0
	v_mov_b64_e32 v[66:67], 0
	v_mov_b64_e32 v[4:5], 0
	v_mov_b64_e32 v[6:7], 0
	v_mov_b64_e32 v[68:69], 0
	v_mov_b64_e32 v[70:71], 0
	v_mov_b64_e32 v[12:13], 0
	v_mov_b64_e32 v[14:15], 0
	v_mov_b64_e32 v[72:73], 0
	v_mov_b64_e32 v[74:75], 0
	v_mov_b64_e32 v[24:25], 0
	v_mov_b64_e32 v[26:27], 0
	v_mov_b64_e32 v[76:77], 0
	v_mov_b64_e32 v[78:79], 0
	v_mov_b64_e32 v[8:9], 0
	v_mov_b64_e32 v[10:11], 0
	v_mov_b64_e32 v[80:81], 0
	v_mov_b64_e32 v[82:83], 0
	v_mov_b64_e32 v[20:21], 0
	v_mov_b64_e32 v[22:23], 0
	v_mov_b64_e32 v[84:85], 0
	v_mov_b64_e32 v[86:87], 0
	v_mov_b64_e32 v[16:17], 0
	v_mov_b64_e32 v[18:19], 0
	v_mov_b64_e32 v[88:89], 0
	v_mov_b64_e32 v[90:91], 0
	v_mov_b64_e32 v[28:29], 0
	v_mov_b64_e32 v[30:31], 0
	v_mov_b64_e32 v[92:93], 0
	v_mov_b64_e32 v[94:95], 0
	v_mov_b64_e32 v[32:33], 0
	v_mov_b64_e32 v[34:35], 0
	v_mov_b64_e32 v[96:97], 0
	v_mov_b64_e32 v[98:99], 0
	v_mov_b64_e32 v[36:37], 0
	v_mov_b64_e32 v[38:39], 0
	v_mov_b64_e32 v[100:101], 0
	v_mov_b64_e32 v[102:103], 0
	v_mov_b64_e32 v[40:41], 0
	v_mov_b64_e32 v[42:43], 0
	v_mov_b64_e32 v[104:105], 0
	v_mov_b64_e32 v[106:107], 0
	v_mov_b64_e32 v[44:45], 0
	v_mov_b64_e32 v[46:47], 0
	v_mov_b64_e32 v[108:109], 0
	v_mov_b64_e32 v[110:111], 0
	v_mov_b64_e32 v[48:49], 0
	v_mov_b64_e32 v[50:51], 0
	v_mov_b64_e32 v[112:113], 0
	v_mov_b64_e32 v[114:115], 0
	v_mov_b64_e32 v[52:53], 0
	v_mov_b64_e32 v[54:55], 0
	v_mov_b64_e32 v[116:117], 0
	v_mov_b64_e32 v[118:119], 0
	v_mov_b64_e32 v[56:57], 0
	v_mov_b64_e32 v[58:59], 0
	v_mov_b64_e32 v[120:121], 0
	v_mov_b64_e32 v[122:123], 0
	v_mov_b64_e32 v[60:61], 0
	v_mov_b64_e32 v[62:63], 0
	v_mov_b64_e32 v[124:125], 0
	v_mov_b64_e32 v[126:127], 0

.LBB0_1289:
	s_add_u32 s4, s36, 0x100
	s_addc_u32 s5, s37, 0
	s_add_u32 s15, s34, 0x100
	s_addc_u32 s17, s35, 0
	s_add_u32 s34, s36, 0x80080
	v_mov_b64_e32 v[0:1], 0
	s_addc_u32 s35, s37, 0
	s_mov_b32 s21, -2
	v_mov_b64_e32 v[2:3], 0
	v_mov_b64_e32 v[4:5], 0
	v_mov_b64_e32 v[6:7], 0
	v_mov_b64_e32 v[8:9], 0
	v_mov_b64_e32 v[10:11], 0
	v_mov_b64_e32 v[16:17], 0
	v_mov_b64_e32 v[18:19], 0
	v_mov_b64_e32 v[24:25], 0
	v_mov_b64_e32 v[26:27], 0
	v_mov_b64_e32 v[32:33], 0
	v_mov_b64_e32 v[34:35], 0
	v_mov_b64_e32 v[40:41], 0
	v_mov_b64_e32 v[42:43], 0
	v_mov_b64_e32 v[48:49], 0
	v_mov_b64_e32 v[50:51], 0
	v_mov_b64_e32 v[12:13], 0
	v_mov_b64_e32 v[14:15], 0
	v_mov_b64_e32 v[20:21], 0
	v_mov_b64_e32 v[22:23], 0
	v_mov_b64_e32 v[28:29], 0
	v_mov_b64_e32 v[30:31], 0
	v_mov_b64_e32 v[36:37], 0
	v_mov_b64_e32 v[38:39], 0
	v_mov_b64_e32 v[44:45], 0
	v_mov_b64_e32 v[46:47], 0
	v_mov_b64_e32 v[52:53], 0
	v_mov_b64_e32 v[54:55], 0
	v_mov_b64_e32 v[56:57], 0
	v_mov_b64_e32 v[58:59], 0
	v_mov_b64_e32 v[60:61], 0
	v_mov_b64_e32 v[62:63], 0
	v_mov_b64_e32 v[64:65], 0
	v_mov_b64_e32 v[66:67], 0
	v_mov_b64_e32 v[68:69], 0
	v_mov_b64_e32 v[70:71], 0
	v_mov_b64_e32 v[72:73], 0
	v_mov_b64_e32 v[74:75], 0
	v_mov_b64_e32 v[80:81], 0
	v_mov_b64_e32 v[82:83], 0
	v_mov_b64_e32 v[88:89], 0
	v_mov_b64_e32 v[90:91], 0
	v_mov_b64_e32 v[96:97], 0
	v_mov_b64_e32 v[98:99], 0
	v_mov_b64_e32 v[104:105], 0
	v_mov_b64_e32 v[106:107], 0
	v_mov_b64_e32 v[112:113], 0
	v_mov_b64_e32 v[114:115], 0
	v_mov_b64_e32 v[76:77], 0
	v_mov_b64_e32 v[78:79], 0
	v_mov_b64_e32 v[84:85], 0
	v_mov_b64_e32 v[86:87], 0
	v_mov_b64_e32 v[92:93], 0
	v_mov_b64_e32 v[94:95], 0
	v_mov_b64_e32 v[100:101], 0
	v_mov_b64_e32 v[102:103], 0
	v_mov_b64_e32 v[108:109], 0
	v_mov_b64_e32 v[110:111], 0
	v_mov_b64_e32 v[116:117], 0
	v_mov_b64_e32 v[118:119], 0
	v_mov_b64_e32 v[120:121], 0
	v_mov_b64_e32 v[122:123], 0
	v_mov_b64_e32 v[124:125], 0
	v_mov_b64_e32 v[126:127], 0

.LBB0_1424:
	s_add_u32 s4, s80, 0x100
	s_addc_u32 s5, s81, 0
	s_add_u32 s15, s74, 0x100
	s_addc_u32 s72, s75, 0
	s_add_u32 s28, s80, 0x160080
	v_mov_b64_e32 v[0:1], 0
	s_addc_u32 s29, s81, 0
	s_mov_b32 s80, -2
	v_mov_b64_e32 v[2:3], 0
	v_mov_b64_e32 v[4:5], 0
	v_mov_b64_e32 v[6:7], 0
	v_mov_b64_e32 v[12:13], 0
	v_mov_b64_e32 v[14:15], 0
	v_mov_b64_e32 v[20:21], 0
	v_mov_b64_e32 v[22:23], 0
	v_mov_b64_e32 v[28:29], 0
	v_mov_b64_e32 v[30:31], 0
	v_mov_b64_e32 v[36:37], 0
	v_mov_b64_e32 v[38:39], 0
	v_mov_b64_e32 v[44:45], 0
	v_mov_b64_e32 v[46:47], 0
	v_mov_b64_e32 v[52:53], 0
	v_mov_b64_e32 v[54:55], 0
	v_mov_b64_e32 v[8:9], 0
	v_mov_b64_e32 v[10:11], 0
	v_mov_b64_e32 v[16:17], 0
	v_mov_b64_e32 v[18:19], 0
	v_mov_b64_e32 v[24:25], 0
	v_mov_b64_e32 v[26:27], 0
	v_mov_b64_e32 v[32:33], 0
	v_mov_b64_e32 v[34:35], 0
	v_mov_b64_e32 v[40:41], 0
	v_mov_b64_e32 v[42:43], 0
	v_mov_b64_e32 v[48:49], 0
	v_mov_b64_e32 v[50:51], 0
	v_mov_b64_e32 v[56:57], 0
	v_mov_b64_e32 v[58:59], 0
	v_mov_b64_e32 v[60:61], 0
	v_mov_b64_e32 v[62:63], 0
	v_mov_b64_e32 v[64:65], 0
	v_mov_b64_e32 v[66:67], 0
	v_mov_b64_e32 v[68:69], 0
	v_mov_b64_e32 v[70:71], 0
	v_mov_b64_e32 v[76:77], 0
	v_mov_b64_e32 v[78:79], 0
	v_mov_b64_e32 v[80:81], 0
	v_mov_b64_e32 v[82:83], 0
	v_mov_b64_e32 v[92:93], 0
	v_mov_b64_e32 v[94:95], 0
	v_mov_b64_e32 v[100:101], 0
	v_mov_b64_e32 v[102:103], 0
	v_mov_b64_e32 v[108:109], 0
	v_mov_b64_e32 v[110:111], 0
	v_mov_b64_e32 v[112:113], 0
	v_mov_b64_e32 v[114:115], 0
	v_mov_b64_e32 v[72:73], 0
	v_mov_b64_e32 v[74:75], 0
	v_mov_b64_e32 v[84:85], 0
	v_mov_b64_e32 v[86:87], 0
	v_mov_b64_e32 v[88:89], 0
	v_mov_b64_e32 v[90:91], 0
	v_mov_b64_e32 v[96:97], 0
	v_mov_b64_e32 v[98:99], 0
	v_mov_b64_e32 v[104:105], 0
	v_mov_b64_e32 v[106:107], 0
	v_mov_b64_e32 v[116:117], 0
	v_mov_b64_e32 v[118:119], 0
	v_mov_b64_e32 v[128:129], 0
	v_mov_b64_e32 v[130:131], 0
	v_mov_b64_e32 v[140:141], 0
	v_mov_b64_e32 v[142:143], 0

.LBB0_1578:
	s_add_u32 s13, s24, 0x100
	s_addc_u32 s21, s25, 0
	s_add_u32 s47, s22, 0x100
	v_mov_b64_e32 v[0:1], 0
	s_addc_u32 s48, s23, 0
	s_mov_b32 s49, -2
	v_mov_b64_e32 v[2:3], 0
	v_mov_b64_e32 v[4:5], 0
	v_mov_b64_e32 v[6:7], 0
	v_mov_b64_e32 v[12:13], 0
	v_mov_b64_e32 v[14:15], 0
	v_mov_b64_e32 v[16:17], 0
	v_mov_b64_e32 v[18:19], 0
	v_mov_b64_e32 v[24:25], 0
	v_mov_b64_e32 v[26:27], 0
	v_mov_b64_e32 v[32:33], 0
	v_mov_b64_e32 v[34:35], 0
	v_mov_b64_e32 v[40:41], 0
	v_mov_b64_e32 v[42:43], 0
	v_mov_b64_e32 v[48:49], 0
	v_mov_b64_e32 v[50:51], 0
	v_mov_b64_e32 v[8:9], 0
	v_mov_b64_e32 v[10:11], 0
	v_mov_b64_e32 v[20:21], 0
	v_mov_b64_e32 v[22:23], 0
	v_mov_b64_e32 v[28:29], 0
	v_mov_b64_e32 v[30:31], 0
	v_mov_b64_e32 v[36:37], 0
	v_mov_b64_e32 v[38:39], 0
	v_mov_b64_e32 v[44:45], 0
	v_mov_b64_e32 v[46:47], 0
	v_mov_b64_e32 v[52:53], 0
	v_mov_b64_e32 v[54:55], 0
	v_mov_b64_e32 v[56:57], 0
	v_mov_b64_e32 v[58:59], 0
	v_mov_b64_e32 v[60:61], 0
	v_mov_b64_e32 v[62:63], 0
	v_mov_b64_e32 v[64:65], 0
	v_mov_b64_e32 v[66:67], 0
	v_mov_b64_e32 v[68:69], 0
	v_mov_b64_e32 v[70:71], 0
	v_mov_b64_e32 v[80:81], 0
	v_mov_b64_e32 v[82:83], 0
	v_mov_b64_e32 v[84:85], 0
	v_mov_b64_e32 v[86:87], 0
	v_mov_b64_e32 v[96:97], 0
	v_mov_b64_e32 v[98:99], 0
	v_mov_b64_e32 v[100:101], 0
	v_mov_b64_e32 v[102:103], 0
	v_mov_b64_e32 v[116:117], 0
	v_mov_b64_e32 v[118:119], 0
	v_mov_b64_e32 v[124:125], 0
	v_mov_b64_e32 v[126:127], 0
	v_mov_b64_e32 v[72:73], 0
	v_mov_b64_e32 v[74:75], 0
	v_mov_b64_e32 v[76:77], 0
	v_mov_b64_e32 v[78:79], 0
	v_mov_b64_e32 v[88:89], 0
	v_mov_b64_e32 v[90:91], 0
	v_mov_b64_e32 v[92:93], 0
	v_mov_b64_e32 v[94:95], 0
	v_mov_b64_e32 v[104:105], 0
	v_mov_b64_e32 v[106:107], 0
	v_mov_b64_e32 v[108:109], 0
	v_mov_b64_e32 v[110:111], 0
	v_mov_b64_e32 v[136:137], 0
	v_mov_b64_e32 v[138:139], 0
	v_mov_b64_e32 v[140:141], 0
	v_mov_b64_e32 v[142:143], 0
